# nsa unit: prologue issues both bias-table loads + DMAs before one wait; epilogue prefetches the second column block's OCB/gate/window data at the top instead of touch loads
# speedup vs baseline: 1.0147x; 1.0003x over previous
.LBB0_350:
	v_readlane_b32 s4, v255, 18
	v_lshlrev_b32_e32 v0, 1, v138
	v_readlane_b32 s5, v255, 19
	v_lshl_add_u64 v[40:41], v[128:129], 0, v[0:1]
	v_lshl_add_u64 v[38:39], v[130:131], 0, v[0:1]
	v_lshl_add_u64 v[2:3], s[4:5], 0, v[120:121]
	v_lshlrev_b32_e32 v0, 1, v118
	v_lshl_add_u64 v[2:3], v[2:3], 0, v[0:1]
	v_add_co_u32_e32 v2, vcc, 0x1000, v2
	s_waitcnt vmcnt(0) lgkmcnt(0)
	s_nop 0
	v_addc_co_u32_e32 v3, vcc, 0, v3, vcc
	s_barrier
	global_load_dword v80, v[116:117], off
	global_load_dword v81, v[116:117], off offset:1024
	global_load_dwordx4 v[56:59], v[104:105], off
	global_load_dwordx4 v[60:63], v[108:109], off
	global_load_dwordx4 v[64:67], v[110:111], off
	global_load_dwordx4 v[68:71], v[106:107], off
	v_lshlrev_b64 v[90:91], 11, v[114:115]
	v_lshl_add_u64 v[90:91], v[40:41], 0, v[90:91]
	global_load_dword v86, v[90:91], off
	v_lshlrev_b64 v[90:91], 11, v[102:103]
	v_lshl_add_u64 v[90:91], v[40:41], 0, v[90:91]
	global_load_dwordx4 v[76:79], v[90:91], off
	global_load_dwordx4 v[92:95], v[90:91], off offset:16
	v_lshl_add_u64 v[90:91], s[4:5], 0, v[112:113]
	v_lshl_add_u64 v[90:91], v[90:91], 0, v[0:1]
	v_add_co_u32_e32 v90, vcc, s83, v90
	s_nop 1
	v_addc_co_u32_e32 v91, vcc, 0, v91, vcc
	global_load_dword v88, v[90:91], off offset:3586
	global_load_dword v2, v[2:3], off offset:3586
	s_nop 0
	global_load_dwordx4 v[10:13], v[116:117], off offset:2048
	global_load_dwordx4 v[14:17], v[116:117], off offset:3072
	s_waitcnt vmcnt(2)
	v_lshlrev_b32_e32 v3, 16, v2
	v_mul_f32_e32 v3, 0xbfb8aa3b, v3
	v_exp_f32_e32 v3, v3
	v_and_b32_e32 v2, 0xffff0000, v2
	v_mul_f32_e32 v2, 0xbfb8aa3b, v2
	v_exp_f32_e32 v2, v2
	v_add_f32_e32 v3, 1.0, v3
	v_div_scale_f32 v4, s[0:1], v3, v3, 1.0
	v_rcp_f32_e32 v5, v4
	v_add_f32_e32 v55, 1.0, v2
	ds_bpermute_b32 v2, v119, v144
	v_fma_f32 v6, -v4, v5, 1.0
	v_fmac_f32_e32 v5, v6, v5
	v_div_scale_f32 v6, vcc, 1.0, v3, 1.0
	v_mul_f32_e32 v7, v6, v5
	v_fma_f32 v8, -v4, v7, v6
	v_fmac_f32_e32 v7, v8, v5
	v_fma_f32 v4, -v4, v7, v6
	v_div_fmas_f32 v4, v4, v5, v7
	s_waitcnt lgkmcnt(0)
	v_add_f32_e32 v2, v144, v2
	v_div_fixup_f32 v3, v4, v3, 1.0
	ds_bpermute_b32 v4, v137, v2
	s_waitcnt lgkmcnt(0)
	v_add_f32_e32 v2, v2, v4
	v_div_scale_f32 v4, s[0:1], v2, v2, 1.0
	v_rcp_f32_e32 v5, v4
	v_cmp_lt_f32_e64 s[6:7], 0, v2
	v_fma_f32 v6, -v4, v5, 1.0
	v_fmac_f32_e32 v5, v6, v5
	v_div_scale_f32 v6, vcc, 1.0, v2, 1.0
	v_mul_f32_e32 v7, v6, v5
	v_fma_f32 v8, -v4, v7, v6
	v_fmac_f32_e32 v7, v8, v5
	v_fma_f32 v4, -v4, v7, v6
	v_div_fmas_f32 v4, v4, v5, v7
	v_div_fixup_f32 v2, v4, v2, 1.0
	v_cndmask_b32_e64 v2, 0, v2, s[6:7]
	v_mul_f32_e32 v54, v3, v2
	global_load_dwordx4 v[2:5], v[116:117], off
	global_load_dwordx4 v[6:9], v[116:117], off offset:1024
	s_waitcnt vmcnt(3)
	v_pk_fma_f32 v[10:11], v[42:43], v[54:55], v[10:11] op_sel_hi:[1,0,1]
	v_pk_fma_f32 v[12:13], v[44:45], v[54:55], v[12:13] op_sel_hi:[1,0,1]
	s_waitcnt vmcnt(2)
	v_pk_fma_f32 v[16:17], v[52:53], v[54:55], v[16:17] op_sel_hi:[1,0,1]
	v_pk_fma_f32 v[14:15], v[50:51], v[54:55], v[14:15] op_sel_hi:[1,0,1]
	s_waitcnt vmcnt(1)
	v_pk_fma_f32 v[2:3], v[34:35], v[54:55], v[2:3] op_sel_hi:[1,0,1]
	v_div_scale_f32 v34, s[0:1], v55, v55, 1.0
	v_rcp_f32_e32 v35, v34
	v_pk_fma_f32 v[4:5], v[36:37], v[54:55], v[4:5] op_sel_hi:[1,0,1]
	s_waitcnt vmcnt(0)
	v_pk_fma_f32 v[8:9], v[48:49], v[54:55], v[8:9] op_sel_hi:[1,0,1]
	v_pk_fma_f32 v[6:7], v[46:47], v[54:55], v[6:7] op_sel_hi:[1,0,1]
	v_fma_f32 v36, -v34, v35, 1.0
	v_fmac_f32_e32 v35, v36, v35
	v_div_scale_f32 v36, vcc, 1.0, v55, 1.0
	v_mul_f32_e32 v37, v36, v35
	v_fma_f32 v42, -v34, v37, v36
	v_fmac_f32_e32 v37, v42, v35
	v_fma_f32 v34, -v34, v37, v36
	v_div_fmas_f32 v34, v34, v35, v37
	v_add_u32_e32 v35, v214, v213
	ds_write_b128 v35, v[2:5] offset:16384
	ds_write_b128 v35, v[6:9] offset:16448
	ds_write_b128 v35, v[10:13] offset:16512
	ds_write_b128 v35, v[14:17] offset:16576
	s_waitcnt lgkmcnt(0)
	v_add_u32_e32 v36, v214, v215
	ds_read_b128 v[14:17], v36 offset:16384
	ds_read_b128 v[10:13], v36 offset:16400
	ds_read_b128 v[6:9], v36 offset:16416
	ds_read_b128 v[2:5], v36 offset:16432
	s_waitcnt lgkmcnt(0)
	v_lshlrev_b64 v[42:43], 11, v[114:115]
	v_lshl_add_u64 v[46:47], v[40:41], 0, v[42:43]
	global_load_dwordx4 v[42:45], v[46:47], off offset:16
	s_nop 0
	global_load_dwordx4 v[46:49], v[46:47], off
	v_div_fixup_f32 v34, v34, v55, 1.0
	s_waitcnt vmcnt(0)
	v_lshlrev_b32_e32 v50, 16, v46
	v_and_b32_e32 v51, 0xffff0000, v46
	v_lshlrev_b32_e32 v46, 16, v47
	v_and_b32_e32 v47, 0xffff0000, v47
	s_waitcnt lgkmcnt(3)
	v_pk_fma_f32 v[16:17], v[34:35], v[46:47], v[16:17] op_sel_hi:[0,1,1]
	v_lshlrev_b32_e32 v46, 16, v48
	v_and_b32_e32 v47, 0xffff0000, v48
	s_waitcnt lgkmcnt(2)
	v_pk_fma_f32 v[10:11], v[34:35], v[46:47], v[10:11] op_sel_hi:[0,1,1]
	v_lshlrev_b32_e32 v46, 16, v49
	v_and_b32_e32 v47, 0xffff0000, v49
	v_pk_fma_f32 v[12:13], v[34:35], v[46:47], v[12:13] op_sel_hi:[0,1,1]
	v_lshlrev_b32_e32 v46, 16, v42
	v_and_b32_e32 v47, 0xffff0000, v42
	v_lshlrev_b32_e32 v42, 16, v43
	v_and_b32_e32 v43, 0xffff0000, v43
	s_waitcnt lgkmcnt(1)
	v_pk_fma_f32 v[8:9], v[34:35], v[42:43], v[8:9] op_sel_hi:[0,1,1]
	v_lshlrev_b32_e32 v42, 16, v44
	v_and_b32_e32 v43, 0xffff0000, v44
	s_waitcnt lgkmcnt(0)
	v_pk_fma_f32 v[42:43], v[34:35], v[42:43], v[2:3] op_sel_hi:[0,1,1]
	v_lshlrev_b32_e32 v2, 16, v45
	v_and_b32_e32 v3, 0xffff0000, v45
	v_pk_fma_f32 v[14:15], v[34:35], v[50:51], v[14:15] op_sel_hi:[0,1,1]
	v_pk_fma_f32 v[44:45], v[34:35], v[2:3], v[4:5] op_sel_hi:[0,1,1]
	v_lshlrev_b64 v[2:3], 12, v[114:115]
	v_pk_fma_f32 v[6:7], v[34:35], v[46:47], v[6:7] op_sel_hi:[0,1,1]
	v_lshl_add_u64 v[46:47], v[38:39], 0, v[2:3]
	v_cvt_pk_bf16_f32 v2, v14, v15
	v_cvt_pk_bf16_f32 v3, v16, v17
	v_cvt_pk_bf16_f32 v4, v10, v11
	v_cvt_pk_bf16_f32 v5, v12, v13
	v_cvt_pk_bf16_f32 v6, v6, v7
	v_cvt_pk_bf16_f32 v7, v8, v9
	v_cvt_pk_bf16_f32 v8, v42, v43
	v_cvt_pk_bf16_f32 v9, v44, v45
	global_store_dwordx4 v[46:47], v[2:5], off
	global_store_dwordx4 v[46:47], v[6:9], off offset:16
	v_mov_b64_e32 v[14:15], v[56:57]
	v_mov_b64_e32 v[16:17], v[58:59]
	v_lshl_add_u64 v[2:3], s[4:5], 0, v[112:113]
	v_lshl_add_u64 v[2:3], v[2:3], 0, v[0:1]
	v_add_co_u32_e32 v2, vcc, s83, v2
	v_mov_b64_e32 v[10:11], v[60:61]
	v_mov_b64_e32 v[12:13], v[62:63]
	s_nop 0
	v_addc_co_u32_e32 v3, vcc, 0, v3, vcc
	v_mov_b32_e32 v0, v88
	v_lshlrev_b32_e32 v2, 16, v0
	v_mul_f32_e32 v2, 0xbfb8aa3b, v2
	v_exp_f32_e32 v2, v2
	v_and_b32_e32 v0, 0xffff0000, v0
	v_mul_f32_e32 v0, 0xbfb8aa3b, v0
	v_exp_f32_e32 v0, v0
	v_add_f32_e32 v2, 1.0, v2
	v_div_scale_f32 v3, s[0:1], v2, v2, 1.0
	v_rcp_f32_e32 v4, v3
	v_add_f32_e32 v34, 1.0, v0
	ds_bpermute_b32 v0, v119, v145
	v_fma_f32 v5, -v3, v4, 1.0
	v_fmac_f32_e32 v4, v5, v4
	v_div_scale_f32 v5, vcc, 1.0, v2, 1.0
	v_mul_f32_e32 v6, v5, v4
	v_fma_f32 v7, -v3, v6, v5
	v_fmac_f32_e32 v6, v7, v4
	v_fma_f32 v3, -v3, v6, v5
	v_div_fmas_f32 v3, v3, v4, v6
	s_waitcnt lgkmcnt(0)
	v_add_f32_e32 v0, v145, v0
	v_div_fixup_f32 v2, v3, v2, 1.0
	ds_bpermute_b32 v3, v137, v0
	s_waitcnt lgkmcnt(0)
	v_add_f32_e32 v0, v0, v3
	v_div_scale_f32 v3, s[0:1], v0, v0, 1.0
	v_rcp_f32_e32 v4, v3
	v_cmp_lt_f32_e64 s[6:7], 0, v0
	v_fma_f32 v5, -v3, v4, 1.0
	v_fmac_f32_e32 v4, v5, v4
	v_div_scale_f32 v5, vcc, 1.0, v0, 1.0
	v_mul_f32_e32 v6, v5, v4
	v_fma_f32 v7, -v3, v6, v5
	v_fmac_f32_e32 v6, v7, v4
	v_fma_f32 v3, -v3, v6, v5
	v_div_fmas_f32 v3, v3, v4, v6
	v_div_fixup_f32 v0, v3, v0, 1.0
	v_cndmask_b32_e64 v0, 0, v0, s[6:7]
	v_mul_f32_e32 v0, v2, v0
	v_mov_b64_e32 v[2:3], v[64:65]
	v_mov_b64_e32 v[4:5], v[66:67]
	v_mov_b64_e32 v[6:7], v[68:69]
	v_mov_b64_e32 v[8:9], v[70:71]
	v_pk_fma_f32 v[16:17], v[20:21], v[0:1], v[16:17] op_sel_hi:[1,0,1]
	v_pk_fma_f32 v[14:15], v[18:19], v[0:1], v[14:15] op_sel_hi:[1,0,1]
	v_pk_fma_f32 v[12:13], v[24:25], v[0:1], v[12:13] op_sel_hi:[1,0,1]
	v_pk_fma_f32 v[10:11], v[22:23], v[0:1], v[10:11] op_sel_hi:[1,0,1]
	v_pk_fma_f32 v[4:5], v[32:33], v[0:1], v[4:5] op_sel_hi:[1,0,1]
	v_pk_fma_f32 v[2:3], v[30:31], v[0:1], v[2:3] op_sel_hi:[1,0,1]
	v_pk_fma_f32 v[8:9], v[28:29], v[0:1], v[8:9] op_sel_hi:[1,0,1]
	v_pk_fma_f32 v[6:7], v[26:27], v[0:1], v[6:7] op_sel_hi:[1,0,1]
	v_div_scale_f32 v0, s[0:1], v34, v34, 1.0
	v_rcp_f32_e32 v18, v0
	ds_write_b128 v35, v[2:5] offset:16384
	ds_write_b128 v35, v[6:9] offset:16448
	ds_write_b128 v35, v[10:13] offset:16512
	ds_write_b128 v35, v[14:17] offset:16576
	s_waitcnt lgkmcnt(0)
	v_fma_f32 v19, -v0, v18, 1.0
	v_fmac_f32_e32 v18, v19, v18
	v_div_scale_f32 v19, vcc, 1.0, v34, 1.0
	v_mul_f32_e32 v20, v19, v18
	v_fma_f32 v21, -v0, v20, v19
	v_fmac_f32_e32 v20, v21, v18
	v_fma_f32 v0, -v0, v20, v19
	v_div_fmas_f32 v0, v0, v18, v20
	ds_read_b128 v[14:17], v36 offset:16384
	ds_read_b128 v[10:13], v36 offset:16400
	ds_read_b128 v[6:9], v36 offset:16416
	ds_read_b128 v[2:5], v36 offset:16432
	s_waitcnt lgkmcnt(0)
	v_lshlrev_b64 v[18:19], 11, v[102:103]
	v_lshl_add_u64 v[22:23], v[40:41], 0, v[18:19]
	v_mov_b64_e32 v[18:19], v[92:93]
	v_mov_b64_e32 v[20:21], v[94:95]
	s_nop 0
	v_mov_b64_e32 v[22:23], v[76:77]
	v_mov_b64_e32 v[24:25], v[78:79]
	v_div_fixup_f32 v0, v0, v34, 1.0
	v_readlane_b32 s0, v253, 0
	s_add_i32 s33, s33, s0
	s_cmpk_gt_i32 s33, 0x1ff
	v_readlane_b32 s1, v253, 1
	v_lshlrev_b32_e32 v26, 16, v22
	v_and_b32_e32 v27, 0xffff0000, v22
	v_lshlrev_b32_e32 v22, 16, v23
	v_and_b32_e32 v23, 0xffff0000, v23
	s_waitcnt lgkmcnt(3)
	v_pk_fma_f32 v[16:17], v[0:1], v[22:23], v[16:17] op_sel_hi:[0,1,1]
	v_lshlrev_b32_e32 v22, 16, v24
	v_and_b32_e32 v23, 0xffff0000, v24
	s_waitcnt lgkmcnt(2)
	v_pk_fma_f32 v[10:11], v[0:1], v[22:23], v[10:11] op_sel_hi:[0,1,1]
	v_lshlrev_b32_e32 v22, 16, v25
	v_and_b32_e32 v23, 0xffff0000, v25
	v_pk_fma_f32 v[12:13], v[0:1], v[22:23], v[12:13] op_sel_hi:[0,1,1]
	v_lshlrev_b32_e32 v22, 16, v18
	v_and_b32_e32 v23, 0xffff0000, v18
	v_lshlrev_b32_e32 v18, 16, v19
	v_and_b32_e32 v19, 0xffff0000, v19
	s_waitcnt lgkmcnt(1)
	v_pk_fma_f32 v[8:9], v[0:1], v[18:19], v[8:9] op_sel_hi:[0,1,1]
	v_lshlrev_b32_e32 v18, 16, v20
	v_and_b32_e32 v19, 0xffff0000, v20
	s_waitcnt lgkmcnt(0)
	v_pk_fma_f32 v[18:19], v[0:1], v[18:19], v[2:3] op_sel_hi:[0,1,1]
	v_lshlrev_b32_e32 v2, 16, v21
	v_and_b32_e32 v3, 0xffff0000, v21
	v_pk_fma_f32 v[14:15], v[0:1], v[26:27], v[14:15] op_sel_hi:[0,1,1]
	v_pk_fma_f32 v[20:21], v[0:1], v[2:3], v[4:5] op_sel_hi:[0,1,1]
	v_lshlrev_b64 v[2:3], 12, v[102:103]
	v_pk_fma_f32 v[6:7], v[0:1], v[22:23], v[6:7] op_sel_hi:[0,1,1]
	v_lshl_add_u64 v[22:23], v[38:39], 0, v[2:3]
	v_cvt_pk_bf16_f32 v2, v14, v15
	v_cvt_pk_bf16_f32 v3, v16, v17
	v_cvt_pk_bf16_f32 v4, v10, v11
	v_cvt_pk_bf16_f32 v5, v12, v13
	v_cvt_pk_bf16_f32 v6, v6, v7
	v_cvt_pk_bf16_f32 v7, v8, v9
	v_cvt_pk_bf16_f32 v8, v18, v19
	v_cvt_pk_bf16_f32 v9, v20, v21
	global_store_dwordx4 v[22:23], v[2:5], off
	global_store_dwordx4 v[22:23], v[6:9], off offset:16
	s_cbranch_scc1 .LBB0_451
.LBB0_351:
	s_sub_i32 s0, 0x2ff, s33
	s_cmpk_lt_i32 s33, 0x100
	v_readlane_b32 s1, v254, 33
	v_readlane_b32 s2, v254, 34
	s_cselect_b32 s1, s1, s2
	s_cselect_b32 s2, s33, s0
	v_readlane_b32 s0, v254, 32
	s_add_i32 s4, s1, s0
	v_readlane_b32 s0, v254, 49
	v_readlane_b32 s1, v254, 50
	s_and_b64 s[0:1], s[0:1], exec
	s_cselect_b32 s25, s4, s2
	s_bfe_u32 s1, s25, 0x20006
	s_lshl_b32 s16, s1, 14
	v_lshl_add_u64 v[6:7], v[132:133], 0, s[16:17]
	s_barrier
	global_load_dwordx4 v[24:27], v[6:7], off
	v_add_co_u32_e32 v18, vcc, 0x2000, v6
	s_nop 1
	v_addc_co_u32_e32 v19, vcc, 0, v7, vcc
	global_load_dwordx4 v[28:31], v[18:19], off
	s_movk_i32 s2, 0x2000
	s_ashr_i32 s4, s25, 8
	s_lshl_b32 s6, s4, 10
	s_lshl_b32 s7, s1, 8
	s_or_b32 s6, s6, s7
	s_bfe_u32 s16, s25, 0x20004
	s_ashr_i32 s7, s6, 31
	s_lshl_b32 s5, s16, 13
	s_lshl_b64 s[6:7], s[6:7], 7
	s_and_b32 s0, s25, 63
	s_addk_i32 s5, 0x2000
	s_mov_b32 s2, 0
	v_lshl_add_u64 v[2:3], v[134:135], 0, s[6:7]
.LBB0_352:
	s_add_i32 s8, s15, s2
	s_mov_b64 s[6:7], 0x40000
	s_add_i32 m0, s8, 0x4000
	v_lshl_add_u64 v[4:5], v[2:3], 0, s[6:7]
	global_load_lds_dwordx4 v[2:3], off
	s_add_i32 m0, s8, 0xc000
	s_addk_i32 s2, 0x2000
	global_load_lds_dwordx4 v[4:5], off
	s_mov_b64 s[6:7], 0x2000
	s_cmp_eq_u32 s5, s2
	v_lshl_add_u64 v[2:3], v[2:3], 0, s[6:7]
	s_cbranch_scc0 .LBB0_352
	s_lshl_b32 s22, s4, 12
	s_lshl_b32 s14, s0, 6
	v_readlane_b32 s2, v255, 20
	s_ashr_i32 s23, s22, 31
	s_add_i32 s2, s14, s2
	s_lshl_b64 s[4:5], s[22:23], 13
	v_readlane_b32 s6, v255, 18
	v_lshl_or_b32 v145, s1, 2, v191
	v_readlane_b32 s7, v255, 19
	s_add_u32 s20, s6, s4
	v_or_b32_e32 v140, s2, v122
	s_addc_u32 s21, s7, s5
	v_lshlrev_b32_e32 v0, 7, v145
	v_or_b32_e32 v142, 4, v140
	v_lshl_add_u64 v[2:3], s[20:21], 0, v[0:1]
	v_mov_b32_e32 v137, v1
	v_ashrrev_i32_e32 v141, 31, v140
	v_ashrrev_i32_e32 v143, 31, v142
	v_lshl_add_u64 v[10:11], v[2:3], 0, v[136:137]
	v_lshlrev_b64 v[2:3], 13, v[140:141]
	v_lshlrev_b64 v[12:13], 13, v[142:143]
	v_lshl_add_u64 v[6:7], v[10:11], 0, v[2:3]
	v_lshl_add_u64 v[14:15], v[10:11], 0, v[12:13]
	global_load_dwordx4 v[2:5], v[6:7], off
	s_nop 0
	global_load_dwordx4 v[6:9], v[6:7], off offset:64
	s_nop 0
	global_load_dwordx4 v[10:13], v[14:15], off
	s_nop 0
	global_load_dwordx4 v[14:17], v[14:15], off offset:64
	s_waitcnt vmcnt(0)
	ds_write_b128 v192, v[24:27]
	ds_write_b128 v192, v[28:31] offset:8192
	s_sub_i32 s5, s2, 31
	v_mov_b32_e32 v20, v1
	v_mov_b32_e32 v21, v1
	s_or_b32 s4, s2, 7
	v_add_u32_e32 v137, s5, v123
	v_add_u32_e32 v144, s5, v122
	v_lshlrev_b32_e32 v143, 2, v140
	s_lshl_b32 s13, s16, 10
	v_mov_b32_e32 v0, v1
	v_mov_b32_e32 v18, v1
	v_mov_b32_e32 v19, v1
	v_mov_b64_e32 v[24:25], v[20:21]
	v_mov_b64_e32 v[28:29], v[20:21]
	v_mov_b64_e32 v[32:33], v[20:21]
	v_mov_b64_e32 v[36:37], v[20:21]
	v_mov_b64_e32 v[40:41], v[20:21]
	v_mov_b64_e32 v[44:45], v[20:21]
	v_mov_b64_e32 v[48:49], v[20:21]
	v_lshlrev_b32_e32 v138, 6, v145
	s_add_i32 s23, s2, 0xfffffbf1
	s_sub_i32 s12, 0x41f, s4
	v_mov_b32_e32 v158, v144
	v_mov_b32_e32 v139, v144
	v_mov_b32_e32 v160, v137
	v_mov_b32_e32 v141, v137
	v_sub_u32_e32 v149, v217, v143
	s_addk_i32 s13, 0x400
	v_mov_b32_e32 v238, 0xf149f2ca
	s_mov_b32 s18, 0
	v_mov_b32_e32 v159, v197
	s_mov_b32 s19, 0
	v_mov_b32_e32 v230, v223
	v_mov_b32_e32 v231, v222
	v_mov_b32_e32 v232, v221
	v_mov_b32_e32 v233, v220
	v_mov_b32_e32 v234, v219
	v_mov_b32_e32 v235, v218
	v_mov_b64_e32 v[22:23], v[18:19]
	v_mov_b64_e32 v[26:27], v[18:19]
	v_mov_b64_e32 v[30:31], v[18:19]
	v_mov_b64_e32 v[34:35], v[18:19]
	v_mov_b64_e32 v[38:39], v[18:19]
	v_mov_b64_e32 v[42:43], v[18:19]
	v_mov_b64_e32 v[46:47], v[18:19]
	s_mov_b32 s4, 0
	v_mov_b64_e32 v[162:163], v[0:1]
	v_mov_b32_e32 v0, 0xf149f2ca
	s_waitcnt vmcnt(0) lgkmcnt(0)
	s_barrier
